# P11 silu epilogue: r^2 scale folded into the sigmoid reciprocal (rcp(e*q+q), q=1/r^2): 4 packed ops per output pair instead of 5
# baseline (speedup 1.0000x reference)
.LBB0_1307:
	s_lshl_b32 s20, s20, 7
	s_ashr_i32 s21, s20, 31
	s_lshl_b64 s[20:21], s[20:21], 1
	v_mov_b64_e32 v[150:151], s[66:67]
	v_mad_i64_i32 v[152:153], s[22:23], v148, s36, v[150:151]
	v_lshl_add_u64 v[152:153], v[152:153], 0, s[20:21]
	v_and_b32_e32 v150, 0xf0, v136
	v_mov_b32_e32 v151, 0
	v_lshl_add_u64 v[152:153], v[152:153], 0, v[150:151]
	s_mov_b32 s23, 0
	v_mul_f32_e32 v154, 0xbfb8aa3b, v236
	v_mul_f32_e32 v156, v236, v236
	v_rcp_f32_e32 v156, v156
	v_pk_mul_f32 v[158:159], v[116:117], v[154:155] op_sel_hi:[1,0]
	v_pk_mul_f32 v[160:161], v[118:119], v[154:155] op_sel_hi:[1,0]
	v_pk_mul_f32 v[162:163], v[112:113], v[154:155] op_sel_hi:[1,0]
	v_pk_mul_f32 v[164:165], v[114:115], v[154:155] op_sel_hi:[1,0]
	v_exp_f32_e32 v158, v158
	v_exp_f32_e32 v159, v159
	v_exp_f32_e32 v160, v160
	v_exp_f32_e32 v161, v161
	v_exp_f32_e32 v162, v162
	v_exp_f32_e32 v163, v163
	v_exp_f32_e32 v164, v164
	v_exp_f32_e32 v165, v165
	v_pk_mul_f32 v[124:125], v[116:117], v[124:125]
	v_pk_mul_f32 v[126:127], v[118:119], v[126:127]
	v_pk_mul_f32 v[120:121], v[112:113], v[120:121]
	v_pk_mul_f32 v[122:123], v[114:115], v[122:123]
	v_pk_fma_f32 v[158:159], v[158:159], v[156:157], v[156:157] op_sel_hi:[1,0,0]
	v_pk_fma_f32 v[160:161], v[160:161], v[156:157], v[156:157] op_sel_hi:[1,0,0]
	v_pk_fma_f32 v[162:163], v[162:163], v[156:157], v[156:157] op_sel_hi:[1,0,0]
	v_pk_fma_f32 v[164:165], v[164:165], v[156:157], v[156:157] op_sel_hi:[1,0,0]
	v_rcp_f32_e32 v158, v158
	v_rcp_f32_e32 v159, v159
	v_rcp_f32_e32 v160, v160
	v_rcp_f32_e32 v161, v161
	v_rcp_f32_e32 v162, v162
	v_rcp_f32_e32 v163, v163
	v_rcp_f32_e32 v164, v164
	v_rcp_f32_e32 v165, v165
	v_pk_mul_f32 v[124:125], v[124:125], v[158:159]
	v_pk_mul_f32 v[126:127], v[126:127], v[160:161]
	v_pk_mul_f32 v[120:121], v[120:121], v[162:163]
	v_pk_mul_f32 v[122:123], v[122:123], v[164:165]
	v_cvt_pk_bf16_f32 v116, v124, v125
	v_cvt_pk_bf16_f32 v117, v126, v127
	v_cvt_pk_bf16_f32 v118, v120, v121
	v_cvt_pk_bf16_f32 v119, v122, v123
	global_store_dwordx4 v[152:153], v[116:119], off
	v_mul_f32_e32 v154, 0xbfb8aa3b, v237
	v_mul_f32_e32 v156, v237, v237
	v_rcp_f32_e32 v156, v156
	v_pk_mul_f32 v[158:159], v[100:101], v[154:155] op_sel_hi:[1,0]
	v_pk_mul_f32 v[160:161], v[102:103], v[154:155] op_sel_hi:[1,0]
	v_pk_mul_f32 v[162:163], v[96:97], v[154:155] op_sel_hi:[1,0]
	v_pk_mul_f32 v[164:165], v[98:99], v[154:155] op_sel_hi:[1,0]
	v_exp_f32_e32 v158, v158
	v_exp_f32_e32 v159, v159
	v_exp_f32_e32 v160, v160
	v_exp_f32_e32 v161, v161
	v_exp_f32_e32 v162, v162
	v_exp_f32_e32 v163, v163
	v_exp_f32_e32 v164, v164
	v_exp_f32_e32 v165, v165
	v_pk_mul_f32 v[108:109], v[100:101], v[108:109]
	v_pk_mul_f32 v[110:111], v[102:103], v[110:111]
	v_pk_mul_f32 v[104:105], v[96:97], v[104:105]
	v_pk_mul_f32 v[106:107], v[98:99], v[106:107]
	v_pk_fma_f32 v[158:159], v[158:159], v[156:157], v[156:157] op_sel_hi:[1,0,0]
	v_pk_fma_f32 v[160:161], v[160:161], v[156:157], v[156:157] op_sel_hi:[1,0,0]
	v_pk_fma_f32 v[162:163], v[162:163], v[156:157], v[156:157] op_sel_hi:[1,0,0]
	v_pk_fma_f32 v[164:165], v[164:165], v[156:157], v[156:157] op_sel_hi:[1,0,0]
	v_rcp_f32_e32 v158, v158
	v_rcp_f32_e32 v159, v159
	v_rcp_f32_e32 v160, v160
	v_rcp_f32_e32 v161, v161
	v_rcp_f32_e32 v162, v162
	v_rcp_f32_e32 v163, v163
	v_rcp_f32_e32 v164, v164
	v_rcp_f32_e32 v165, v165
	v_pk_mul_f32 v[108:109], v[108:109], v[158:159]
	v_pk_mul_f32 v[110:111], v[110:111], v[160:161]
	v_pk_mul_f32 v[104:105], v[104:105], v[162:163]
	v_pk_mul_f32 v[106:107], v[106:107], v[164:165]
	v_cvt_pk_bf16_f32 v100, v108, v109
	v_cvt_pk_bf16_f32 v101, v110, v111
	v_cvt_pk_bf16_f32 v102, v104, v105
	v_cvt_pk_bf16_f32 v103, v106, v107
	s_mov_b32 s22, 0x16000
	v_lshl_add_u64 v[96:97], v[152:153], 0, s[22:23]
	global_store_dwordx4 v[96:97], v[100:103], off
	v_mul_f32_e32 v154, 0xbfb8aa3b, v238
	v_mul_f32_e32 v156, v238, v238
	v_rcp_f32_e32 v156, v156
	v_pk_mul_f32 v[158:159], v[84:85], v[154:155] op_sel_hi:[1,0]
	v_pk_mul_f32 v[160:161], v[86:87], v[154:155] op_sel_hi:[1,0]
	v_pk_mul_f32 v[162:163], v[80:81], v[154:155] op_sel_hi:[1,0]
	v_pk_mul_f32 v[164:165], v[82:83], v[154:155] op_sel_hi:[1,0]
	v_exp_f32_e32 v158, v158
	v_exp_f32_e32 v159, v159
	v_exp_f32_e32 v160, v160
	v_exp_f32_e32 v161, v161
	v_exp_f32_e32 v162, v162
	v_exp_f32_e32 v163, v163
	v_exp_f32_e32 v164, v164
	v_exp_f32_e32 v165, v165
	v_pk_mul_f32 v[92:93], v[84:85], v[92:93]
	v_pk_mul_f32 v[94:95], v[86:87], v[94:95]
	v_pk_mul_f32 v[88:89], v[80:81], v[88:89]
	v_pk_mul_f32 v[90:91], v[82:83], v[90:91]
	v_pk_fma_f32 v[158:159], v[158:159], v[156:157], v[156:157] op_sel_hi:[1,0,0]
	v_pk_fma_f32 v[160:161], v[160:161], v[156:157], v[156:157] op_sel_hi:[1,0,0]
	v_pk_fma_f32 v[162:163], v[162:163], v[156:157], v[156:157] op_sel_hi:[1,0,0]
	v_pk_fma_f32 v[164:165], v[164:165], v[156:157], v[156:157] op_sel_hi:[1,0,0]
	v_rcp_f32_e32 v158, v158
	v_rcp_f32_e32 v159, v159
	v_rcp_f32_e32 v160, v160
	v_rcp_f32_e32 v161, v161
	v_rcp_f32_e32 v162, v162
	v_rcp_f32_e32 v163, v163
	v_rcp_f32_e32 v164, v164
	v_rcp_f32_e32 v165, v165
	v_pk_mul_f32 v[92:93], v[92:93], v[158:159]
	v_pk_mul_f32 v[94:95], v[94:95], v[160:161]
	v_pk_mul_f32 v[88:89], v[88:89], v[162:163]
	v_pk_mul_f32 v[90:91], v[90:91], v[164:165]
	v_cvt_pk_bf16_f32 v84, v92, v93
	v_cvt_pk_bf16_f32 v85, v94, v95
	v_cvt_pk_bf16_f32 v86, v88, v89
	v_cvt_pk_bf16_f32 v87, v90, v91
	s_mov_b32 s22, 0x2c000
	v_lshl_add_u64 v[80:81], v[152:153], 0, s[22:23]
	global_store_dwordx4 v[80:81], v[84:87], off
	v_mul_f32_e32 v154, 0xbfb8aa3b, v239
	v_mul_f32_e32 v156, v239, v239
	v_rcp_f32_e32 v156, v156
	v_pk_mul_f32 v[158:159], v[68:69], v[154:155] op_sel_hi:[1,0]
	v_pk_mul_f32 v[160:161], v[70:71], v[154:155] op_sel_hi:[1,0]
	v_pk_mul_f32 v[162:163], v[64:65], v[154:155] op_sel_hi:[1,0]
	v_pk_mul_f32 v[164:165], v[66:67], v[154:155] op_sel_hi:[1,0]
	v_exp_f32_e32 v158, v158
	v_exp_f32_e32 v159, v159
	v_exp_f32_e32 v160, v160
	v_exp_f32_e32 v161, v161
	v_exp_f32_e32 v162, v162
	v_exp_f32_e32 v163, v163
	v_exp_f32_e32 v164, v164
	v_exp_f32_e32 v165, v165
	v_pk_mul_f32 v[76:77], v[68:69], v[76:77]
	v_pk_mul_f32 v[78:79], v[70:71], v[78:79]
	v_pk_mul_f32 v[72:73], v[64:65], v[72:73]
	v_pk_mul_f32 v[74:75], v[66:67], v[74:75]
	v_pk_fma_f32 v[158:159], v[158:159], v[156:157], v[156:157] op_sel_hi:[1,0,0]
	v_pk_fma_f32 v[160:161], v[160:161], v[156:157], v[156:157] op_sel_hi:[1,0,0]
	v_pk_fma_f32 v[162:163], v[162:163], v[156:157], v[156:157] op_sel_hi:[1,0,0]
	v_pk_fma_f32 v[164:165], v[164:165], v[156:157], v[156:157] op_sel_hi:[1,0,0]
	v_rcp_f32_e32 v158, v158
	v_rcp_f32_e32 v159, v159
	v_rcp_f32_e32 v160, v160
	v_rcp_f32_e32 v161, v161
	v_rcp_f32_e32 v162, v162
	v_rcp_f32_e32 v163, v163
	v_rcp_f32_e32 v164, v164
	v_rcp_f32_e32 v165, v165
	v_pk_mul_f32 v[76:77], v[76:77], v[158:159]
	v_pk_mul_f32 v[78:79], v[78:79], v[160:161]
	v_pk_mul_f32 v[72:73], v[72:73], v[162:163]
	v_pk_mul_f32 v[74:75], v[74:75], v[164:165]
	v_cvt_pk_bf16_f32 v68, v76, v77
	v_cvt_pk_bf16_f32 v69, v78, v79
	v_cvt_pk_bf16_f32 v70, v72, v73
	v_cvt_pk_bf16_f32 v71, v74, v75
	s_mov_b32 s22, 0x42000
	v_lshl_add_u64 v[64:65], v[152:153], 0, s[22:23]
	global_store_dwordx4 v[64:65], v[68:71], off
	v_mul_f32_e32 v154, 0xbfb8aa3b, v240
	v_mul_f32_e32 v156, v240, v240
	v_rcp_f32_e32 v156, v156
	v_pk_mul_f32 v[158:159], v[52:53], v[154:155] op_sel_hi:[1,0]
	v_pk_mul_f32 v[160:161], v[54:55], v[154:155] op_sel_hi:[1,0]
	v_pk_mul_f32 v[162:163], v[48:49], v[154:155] op_sel_hi:[1,0]
	v_pk_mul_f32 v[164:165], v[50:51], v[154:155] op_sel_hi:[1,0]
	v_exp_f32_e32 v158, v158
	v_exp_f32_e32 v159, v159
	v_exp_f32_e32 v160, v160
	v_exp_f32_e32 v161, v161
	v_exp_f32_e32 v162, v162
	v_exp_f32_e32 v163, v163
	v_exp_f32_e32 v164, v164
	v_exp_f32_e32 v165, v165
	v_pk_mul_f32 v[60:61], v[52:53], v[60:61]
	v_pk_mul_f32 v[62:63], v[54:55], v[62:63]
	v_pk_mul_f32 v[56:57], v[48:49], v[56:57]
	v_pk_mul_f32 v[58:59], v[50:51], v[58:59]
	v_pk_fma_f32 v[158:159], v[158:159], v[156:157], v[156:157] op_sel_hi:[1,0,0]
	v_pk_fma_f32 v[160:161], v[160:161], v[156:157], v[156:157] op_sel_hi:[1,0,0]
	v_pk_fma_f32 v[162:163], v[162:163], v[156:157], v[156:157] op_sel_hi:[1,0,0]
	v_pk_fma_f32 v[164:165], v[164:165], v[156:157], v[156:157] op_sel_hi:[1,0,0]
	v_rcp_f32_e32 v158, v158
	v_rcp_f32_e32 v159, v159
	v_rcp_f32_e32 v160, v160
	v_rcp_f32_e32 v161, v161
	v_rcp_f32_e32 v162, v162
	v_rcp_f32_e32 v163, v163
	v_rcp_f32_e32 v164, v164
	v_rcp_f32_e32 v165, v165
	v_pk_mul_f32 v[60:61], v[60:61], v[158:159]
	v_pk_mul_f32 v[62:63], v[62:63], v[160:161]
	v_pk_mul_f32 v[56:57], v[56:57], v[162:163]
	v_pk_mul_f32 v[58:59], v[58:59], v[164:165]
	v_cvt_pk_bf16_f32 v52, v60, v61
	v_cvt_pk_bf16_f32 v53, v62, v63
	v_cvt_pk_bf16_f32 v54, v56, v57
	v_cvt_pk_bf16_f32 v55, v58, v59
	s_mov_b32 s22, 0xb0000
	v_lshl_add_u64 v[48:49], v[152:153], 0, s[22:23]
	global_store_dwordx4 v[48:49], v[52:55], off
	v_mul_f32_e32 v154, 0xbfb8aa3b, v241
	v_mul_f32_e32 v156, v241, v241
	v_rcp_f32_e32 v156, v156
	v_pk_mul_f32 v[158:159], v[36:37], v[154:155] op_sel_hi:[1,0]
	v_pk_mul_f32 v[160:161], v[38:39], v[154:155] op_sel_hi:[1,0]
	v_pk_mul_f32 v[162:163], v[32:33], v[154:155] op_sel_hi:[1,0]
	v_pk_mul_f32 v[164:165], v[34:35], v[154:155] op_sel_hi:[1,0]
	v_exp_f32_e32 v158, v158
	v_exp_f32_e32 v159, v159
	v_exp_f32_e32 v160, v160
	v_exp_f32_e32 v161, v161
	v_exp_f32_e32 v162, v162
	v_exp_f32_e32 v163, v163
	v_exp_f32_e32 v164, v164
	v_exp_f32_e32 v165, v165
	v_pk_mul_f32 v[44:45], v[36:37], v[44:45]
	v_pk_mul_f32 v[46:47], v[38:39], v[46:47]
	v_pk_mul_f32 v[40:41], v[32:33], v[40:41]
	v_pk_mul_f32 v[42:43], v[34:35], v[42:43]
	v_pk_fma_f32 v[158:159], v[158:159], v[156:157], v[156:157] op_sel_hi:[1,0,0]
	v_pk_fma_f32 v[160:161], v[160:161], v[156:157], v[156:157] op_sel_hi:[1,0,0]
	v_pk_fma_f32 v[162:163], v[162:163], v[156:157], v[156:157] op_sel_hi:[1,0,0]
	v_pk_fma_f32 v[164:165], v[164:165], v[156:157], v[156:157] op_sel_hi:[1,0,0]
	v_rcp_f32_e32 v158, v158
	v_rcp_f32_e32 v159, v159
	v_rcp_f32_e32 v160, v160
	v_rcp_f32_e32 v161, v161
	v_rcp_f32_e32 v162, v162
	v_rcp_f32_e32 v163, v163
	v_rcp_f32_e32 v164, v164
	v_rcp_f32_e32 v165, v165
	v_pk_mul_f32 v[44:45], v[44:45], v[158:159]
	v_pk_mul_f32 v[46:47], v[46:47], v[160:161]
	v_pk_mul_f32 v[40:41], v[40:41], v[162:163]
	v_pk_mul_f32 v[42:43], v[42:43], v[164:165]
	v_cvt_pk_bf16_f32 v36, v44, v45
	v_cvt_pk_bf16_f32 v37, v46, v47
	v_cvt_pk_bf16_f32 v38, v40, v41
	v_cvt_pk_bf16_f32 v39, v42, v43
	s_mov_b32 s22, 0xc6000
	v_lshl_add_u64 v[32:33], v[152:153], 0, s[22:23]
	global_store_dwordx4 v[32:33], v[36:39], off
	v_mul_f32_e32 v154, 0xbfb8aa3b, v242
	v_mul_f32_e32 v156, v242, v242
	v_rcp_f32_e32 v156, v156
	v_pk_mul_f32 v[158:159], v[20:21], v[154:155] op_sel_hi:[1,0]
	v_pk_mul_f32 v[160:161], v[22:23], v[154:155] op_sel_hi:[1,0]
	v_pk_mul_f32 v[162:163], v[16:17], v[154:155] op_sel_hi:[1,0]
	v_pk_mul_f32 v[164:165], v[18:19], v[154:155] op_sel_hi:[1,0]
	v_exp_f32_e32 v158, v158
	v_exp_f32_e32 v159, v159
	v_exp_f32_e32 v160, v160
	v_exp_f32_e32 v161, v161
	v_exp_f32_e32 v162, v162
	v_exp_f32_e32 v163, v163
	v_exp_f32_e32 v164, v164
	v_exp_f32_e32 v165, v165
	v_pk_mul_f32 v[28:29], v[20:21], v[28:29]
	v_pk_mul_f32 v[30:31], v[22:23], v[30:31]
	v_pk_mul_f32 v[24:25], v[16:17], v[24:25]
	v_pk_mul_f32 v[26:27], v[18:19], v[26:27]
	v_pk_fma_f32 v[158:159], v[158:159], v[156:157], v[156:157] op_sel_hi:[1,0,0]
	v_pk_fma_f32 v[160:161], v[160:161], v[156:157], v[156:157] op_sel_hi:[1,0,0]
	v_pk_fma_f32 v[162:163], v[162:163], v[156:157], v[156:157] op_sel_hi:[1,0,0]
	v_pk_fma_f32 v[164:165], v[164:165], v[156:157], v[156:157] op_sel_hi:[1,0,0]
	v_rcp_f32_e32 v158, v158
	v_rcp_f32_e32 v159, v159
	v_rcp_f32_e32 v160, v160
	v_rcp_f32_e32 v161, v161
	v_rcp_f32_e32 v162, v162
	v_rcp_f32_e32 v163, v163
	v_rcp_f32_e32 v164, v164
	v_rcp_f32_e32 v165, v165
	v_pk_mul_f32 v[28:29], v[28:29], v[158:159]
	v_pk_mul_f32 v[30:31], v[30:31], v[160:161]
	v_pk_mul_f32 v[24:25], v[24:25], v[162:163]
	v_pk_mul_f32 v[26:27], v[26:27], v[164:165]
	v_cvt_pk_bf16_f32 v20, v28, v29
	v_cvt_pk_bf16_f32 v21, v30, v31
	v_cvt_pk_bf16_f32 v22, v24, v25
	v_cvt_pk_bf16_f32 v23, v26, v27
	s_mov_b32 s22, 0xdc000
	v_lshl_add_u64 v[16:17], v[152:153], 0, s[22:23]
	global_store_dwordx4 v[16:17], v[20:23], off
	v_mul_f32_e32 v154, 0xbfb8aa3b, v243
	v_mul_f32_e32 v156, v243, v243
	v_rcp_f32_e32 v156, v156
	v_pk_mul_f32 v[158:159], v[4:5], v[154:155] op_sel_hi:[1,0]
	v_pk_mul_f32 v[160:161], v[6:7], v[154:155] op_sel_hi:[1,0]
	v_pk_mul_f32 v[162:163], v[0:1], v[154:155] op_sel_hi:[1,0]
	v_pk_mul_f32 v[164:165], v[2:3], v[154:155] op_sel_hi:[1,0]
	v_exp_f32_e32 v158, v158
	v_exp_f32_e32 v159, v159
	v_exp_f32_e32 v160, v160
	v_exp_f32_e32 v161, v161
	v_exp_f32_e32 v162, v162
	v_exp_f32_e32 v163, v163
	v_exp_f32_e32 v164, v164
	v_exp_f32_e32 v165, v165
	v_pk_mul_f32 v[12:13], v[4:5], v[12:13]
	v_pk_mul_f32 v[14:15], v[6:7], v[14:15]
	v_pk_mul_f32 v[8:9], v[0:1], v[8:9]
	v_pk_mul_f32 v[10:11], v[2:3], v[10:11]
	v_pk_fma_f32 v[158:159], v[158:159], v[156:157], v[156:157] op_sel_hi:[1,0,0]
	v_pk_fma_f32 v[160:161], v[160:161], v[156:157], v[156:157] op_sel_hi:[1,0,0]
	v_pk_fma_f32 v[162:163], v[162:163], v[156:157], v[156:157] op_sel_hi:[1,0,0]
	v_pk_fma_f32 v[164:165], v[164:165], v[156:157], v[156:157] op_sel_hi:[1,0,0]
	v_rcp_f32_e32 v158, v158
	v_rcp_f32_e32 v159, v159
	v_rcp_f32_e32 v160, v160
	v_rcp_f32_e32 v161, v161
	v_rcp_f32_e32 v162, v162
	v_rcp_f32_e32 v163, v163
	v_rcp_f32_e32 v164, v164
	v_rcp_f32_e32 v165, v165
	v_pk_mul_f32 v[12:13], v[12:13], v[158:159]
	v_pk_mul_f32 v[14:15], v[14:15], v[160:161]
	v_pk_mul_f32 v[8:9], v[8:9], v[162:163]
	v_pk_mul_f32 v[10:11], v[10:11], v[164:165]
	v_cvt_pk_bf16_f32 v4, v12, v13
	v_cvt_pk_bf16_f32 v5, v14, v15
	v_cvt_pk_bf16_f32 v6, v8, v9
	v_cvt_pk_bf16_f32 v7, v10, v11
	s_mov_b32 s22, 0xf2000
	v_lshl_add_u64 v[0:1], v[152:153], 0, s[22:23]
	global_store_dwordx4 v[0:1], v[4:7], off

.LBB0_1322:
	s_lshl_b32 s40, s20, 7
	s_ashr_i32 s41, s40, 31
	s_lshl_b64 s[40:41], s[40:41], 1
	v_mov_b64_e32 v[150:151], s[66:67]
	v_mad_i64_i32 v[152:153], s[50:51], v148, s36, v[150:151]
	v_lshl_add_u64 v[152:153], v[152:153], 0, s[40:41]
	v_and_b32_e32 v150, 0xf0, v136
	v_mov_b32_e32 v151, 0
	v_lshl_add_u64 v[152:153], v[152:153], 0, v[150:151]
	s_mov_b32 s51, 0
	v_mul_f32_e32 v154, 0xbfb8aa3b, v236
	v_mul_f32_e32 v156, v236, v236
	v_rcp_f32_e32 v156, v156
	v_pk_mul_f32 v[158:159], v[116:117], v[154:155] op_sel_hi:[1,0]
	v_pk_mul_f32 v[160:161], v[118:119], v[154:155] op_sel_hi:[1,0]
	v_pk_mul_f32 v[162:163], v[112:113], v[154:155] op_sel_hi:[1,0]
	v_pk_mul_f32 v[164:165], v[114:115], v[154:155] op_sel_hi:[1,0]
	v_exp_f32_e32 v158, v158
	v_exp_f32_e32 v159, v159
	v_exp_f32_e32 v160, v160
	v_exp_f32_e32 v161, v161
	v_exp_f32_e32 v162, v162
	v_exp_f32_e32 v163, v163
	v_exp_f32_e32 v164, v164
	v_exp_f32_e32 v165, v165
	v_pk_mul_f32 v[124:125], v[116:117], v[124:125]
	v_pk_mul_f32 v[126:127], v[118:119], v[126:127]
	v_pk_mul_f32 v[120:121], v[112:113], v[120:121]
	v_pk_mul_f32 v[122:123], v[114:115], v[122:123]
	v_pk_fma_f32 v[158:159], v[158:159], v[156:157], v[156:157] op_sel_hi:[1,0,0]
	v_pk_fma_f32 v[160:161], v[160:161], v[156:157], v[156:157] op_sel_hi:[1,0,0]
	v_pk_fma_f32 v[162:163], v[162:163], v[156:157], v[156:157] op_sel_hi:[1,0,0]
	v_pk_fma_f32 v[164:165], v[164:165], v[156:157], v[156:157] op_sel_hi:[1,0,0]
	v_rcp_f32_e32 v158, v158
	v_rcp_f32_e32 v159, v159
	v_rcp_f32_e32 v160, v160
	v_rcp_f32_e32 v161, v161
	v_rcp_f32_e32 v162, v162
	v_rcp_f32_e32 v163, v163
	v_rcp_f32_e32 v164, v164
	v_rcp_f32_e32 v165, v165
	v_pk_mul_f32 v[124:125], v[124:125], v[158:159]
	v_pk_mul_f32 v[126:127], v[126:127], v[160:161]
	v_pk_mul_f32 v[120:121], v[120:121], v[162:163]
	v_pk_mul_f32 v[122:123], v[122:123], v[164:165]
	v_cvt_pk_bf16_f32 v116, v124, v125
	v_cvt_pk_bf16_f32 v117, v126, v127
	v_cvt_pk_bf16_f32 v118, v120, v121
	v_cvt_pk_bf16_f32 v119, v122, v123
	global_store_dwordx4 v[152:153], v[116:119], off
	v_mul_f32_e32 v154, 0xbfb8aa3b, v237
	v_mul_f32_e32 v156, v237, v237
	v_rcp_f32_e32 v156, v156
	v_pk_mul_f32 v[158:159], v[100:101], v[154:155] op_sel_hi:[1,0]
	v_pk_mul_f32 v[160:161], v[102:103], v[154:155] op_sel_hi:[1,0]
	v_pk_mul_f32 v[162:163], v[96:97], v[154:155] op_sel_hi:[1,0]
	v_pk_mul_f32 v[164:165], v[98:99], v[154:155] op_sel_hi:[1,0]
	v_exp_f32_e32 v158, v158
	v_exp_f32_e32 v159, v159
	v_exp_f32_e32 v160, v160
	v_exp_f32_e32 v161, v161
	v_exp_f32_e32 v162, v162
	v_exp_f32_e32 v163, v163
	v_exp_f32_e32 v164, v164
	v_exp_f32_e32 v165, v165
	v_pk_mul_f32 v[108:109], v[100:101], v[108:109]
	v_pk_mul_f32 v[110:111], v[102:103], v[110:111]
	v_pk_mul_f32 v[104:105], v[96:97], v[104:105]
	v_pk_mul_f32 v[106:107], v[98:99], v[106:107]
	v_pk_fma_f32 v[158:159], v[158:159], v[156:157], v[156:157] op_sel_hi:[1,0,0]
	v_pk_fma_f32 v[160:161], v[160:161], v[156:157], v[156:157] op_sel_hi:[1,0,0]
	v_pk_fma_f32 v[162:163], v[162:163], v[156:157], v[156:157] op_sel_hi:[1,0,0]
	v_pk_fma_f32 v[164:165], v[164:165], v[156:157], v[156:157] op_sel_hi:[1,0,0]
	v_rcp_f32_e32 v158, v158
	v_rcp_f32_e32 v159, v159
	v_rcp_f32_e32 v160, v160
	v_rcp_f32_e32 v161, v161
	v_rcp_f32_e32 v162, v162
	v_rcp_f32_e32 v163, v163
	v_rcp_f32_e32 v164, v164
	v_rcp_f32_e32 v165, v165
	v_pk_mul_f32 v[108:109], v[108:109], v[158:159]
	v_pk_mul_f32 v[110:111], v[110:111], v[160:161]
	v_pk_mul_f32 v[104:105], v[104:105], v[162:163]
	v_pk_mul_f32 v[106:107], v[106:107], v[164:165]
	v_cvt_pk_bf16_f32 v100, v108, v109
	v_cvt_pk_bf16_f32 v101, v110, v111
	v_cvt_pk_bf16_f32 v102, v104, v105
	v_cvt_pk_bf16_f32 v103, v106, v107
	s_mov_b32 s50, 0x16000
	v_lshl_add_u64 v[96:97], v[152:153], 0, s[50:51]
	global_store_dwordx4 v[96:97], v[100:103], off
	v_mul_f32_e32 v154, 0xbfb8aa3b, v238
	v_mul_f32_e32 v156, v238, v238
	v_rcp_f32_e32 v156, v156
	v_pk_mul_f32 v[158:159], v[84:85], v[154:155] op_sel_hi:[1,0]
	v_pk_mul_f32 v[160:161], v[86:87], v[154:155] op_sel_hi:[1,0]
	v_pk_mul_f32 v[162:163], v[80:81], v[154:155] op_sel_hi:[1,0]
	v_pk_mul_f32 v[164:165], v[82:83], v[154:155] op_sel_hi:[1,0]
	v_exp_f32_e32 v158, v158
	v_exp_f32_e32 v159, v159
	v_exp_f32_e32 v160, v160
	v_exp_f32_e32 v161, v161
	v_exp_f32_e32 v162, v162
	v_exp_f32_e32 v163, v163
	v_exp_f32_e32 v164, v164
	v_exp_f32_e32 v165, v165
	v_pk_mul_f32 v[92:93], v[84:85], v[92:93]
	v_pk_mul_f32 v[94:95], v[86:87], v[94:95]
	v_pk_mul_f32 v[88:89], v[80:81], v[88:89]
	v_pk_mul_f32 v[90:91], v[82:83], v[90:91]
	v_pk_fma_f32 v[158:159], v[158:159], v[156:157], v[156:157] op_sel_hi:[1,0,0]
	v_pk_fma_f32 v[160:161], v[160:161], v[156:157], v[156:157] op_sel_hi:[1,0,0]
	v_pk_fma_f32 v[162:163], v[162:163], v[156:157], v[156:157] op_sel_hi:[1,0,0]
	v_pk_fma_f32 v[164:165], v[164:165], v[156:157], v[156:157] op_sel_hi:[1,0,0]
	v_rcp_f32_e32 v158, v158
	v_rcp_f32_e32 v159, v159
	v_rcp_f32_e32 v160, v160
	v_rcp_f32_e32 v161, v161
	v_rcp_f32_e32 v162, v162
	v_rcp_f32_e32 v163, v163
	v_rcp_f32_e32 v164, v164
	v_rcp_f32_e32 v165, v165
	v_pk_mul_f32 v[92:93], v[92:93], v[158:159]
	v_pk_mul_f32 v[94:95], v[94:95], v[160:161]
	v_pk_mul_f32 v[88:89], v[88:89], v[162:163]
	v_pk_mul_f32 v[90:91], v[90:91], v[164:165]
	v_cvt_pk_bf16_f32 v84, v92, v93
	v_cvt_pk_bf16_f32 v85, v94, v95
	v_cvt_pk_bf16_f32 v86, v88, v89
	v_cvt_pk_bf16_f32 v87, v90, v91
	s_mov_b32 s50, 0x2c000
	v_lshl_add_u64 v[80:81], v[152:153], 0, s[50:51]
	global_store_dwordx4 v[80:81], v[84:87], off
	v_mul_f32_e32 v154, 0xbfb8aa3b, v239
	v_mul_f32_e32 v156, v239, v239
	v_rcp_f32_e32 v156, v156
	v_pk_mul_f32 v[158:159], v[68:69], v[154:155] op_sel_hi:[1,0]
	v_pk_mul_f32 v[160:161], v[70:71], v[154:155] op_sel_hi:[1,0]
	v_pk_mul_f32 v[162:163], v[64:65], v[154:155] op_sel_hi:[1,0]
	v_pk_mul_f32 v[164:165], v[66:67], v[154:155] op_sel_hi:[1,0]
	v_exp_f32_e32 v158, v158
	v_exp_f32_e32 v159, v159
	v_exp_f32_e32 v160, v160
	v_exp_f32_e32 v161, v161
	v_exp_f32_e32 v162, v162
	v_exp_f32_e32 v163, v163
	v_exp_f32_e32 v164, v164
	v_exp_f32_e32 v165, v165
	v_pk_mul_f32 v[76:77], v[68:69], v[76:77]
	v_pk_mul_f32 v[78:79], v[70:71], v[78:79]
	v_pk_mul_f32 v[72:73], v[64:65], v[72:73]
	v_pk_mul_f32 v[74:75], v[66:67], v[74:75]
	v_pk_fma_f32 v[158:159], v[158:159], v[156:157], v[156:157] op_sel_hi:[1,0,0]
	v_pk_fma_f32 v[160:161], v[160:161], v[156:157], v[156:157] op_sel_hi:[1,0,0]
	v_pk_fma_f32 v[162:163], v[162:163], v[156:157], v[156:157] op_sel_hi:[1,0,0]
	v_pk_fma_f32 v[164:165], v[164:165], v[156:157], v[156:157] op_sel_hi:[1,0,0]
	v_rcp_f32_e32 v158, v158
	v_rcp_f32_e32 v159, v159
	v_rcp_f32_e32 v160, v160
	v_rcp_f32_e32 v161, v161
	v_rcp_f32_e32 v162, v162
	v_rcp_f32_e32 v163, v163
	v_rcp_f32_e32 v164, v164
	v_rcp_f32_e32 v165, v165
	v_pk_mul_f32 v[76:77], v[76:77], v[158:159]
	v_pk_mul_f32 v[78:79], v[78:79], v[160:161]
	v_pk_mul_f32 v[72:73], v[72:73], v[162:163]
	v_pk_mul_f32 v[74:75], v[74:75], v[164:165]
	v_cvt_pk_bf16_f32 v68, v76, v77
	v_cvt_pk_bf16_f32 v69, v78, v79
	v_cvt_pk_bf16_f32 v70, v72, v73
	v_cvt_pk_bf16_f32 v71, v74, v75
	s_mov_b32 s50, 0x42000
	v_lshl_add_u64 v[64:65], v[152:153], 0, s[50:51]
	global_store_dwordx4 v[64:65], v[68:71], off
	v_mul_f32_e32 v154, 0xbfb8aa3b, v240
	v_mul_f32_e32 v156, v240, v240
	v_rcp_f32_e32 v156, v156
	v_pk_mul_f32 v[158:159], v[52:53], v[154:155] op_sel_hi:[1,0]
	v_pk_mul_f32 v[160:161], v[54:55], v[154:155] op_sel_hi:[1,0]
	v_pk_mul_f32 v[162:163], v[48:49], v[154:155] op_sel_hi:[1,0]
	v_pk_mul_f32 v[164:165], v[50:51], v[154:155] op_sel_hi:[1,0]
	v_exp_f32_e32 v158, v158
	v_exp_f32_e32 v159, v159
	v_exp_f32_e32 v160, v160
	v_exp_f32_e32 v161, v161
	v_exp_f32_e32 v162, v162
	v_exp_f32_e32 v163, v163
	v_exp_f32_e32 v164, v164
	v_exp_f32_e32 v165, v165
	v_pk_mul_f32 v[60:61], v[52:53], v[60:61]
	v_pk_mul_f32 v[62:63], v[54:55], v[62:63]
	v_pk_mul_f32 v[56:57], v[48:49], v[56:57]
	v_pk_mul_f32 v[58:59], v[50:51], v[58:59]
	v_pk_fma_f32 v[158:159], v[158:159], v[156:157], v[156:157] op_sel_hi:[1,0,0]
	v_pk_fma_f32 v[160:161], v[160:161], v[156:157], v[156:157] op_sel_hi:[1,0,0]
	v_pk_fma_f32 v[162:163], v[162:163], v[156:157], v[156:157] op_sel_hi:[1,0,0]
	v_pk_fma_f32 v[164:165], v[164:165], v[156:157], v[156:157] op_sel_hi:[1,0,0]
	v_rcp_f32_e32 v158, v158
	v_rcp_f32_e32 v159, v159
	v_rcp_f32_e32 v160, v160
	v_rcp_f32_e32 v161, v161
	v_rcp_f32_e32 v162, v162
	v_rcp_f32_e32 v163, v163
	v_rcp_f32_e32 v164, v164
	v_rcp_f32_e32 v165, v165
	v_pk_mul_f32 v[60:61], v[60:61], v[158:159]
	v_pk_mul_f32 v[62:63], v[62:63], v[160:161]
	v_pk_mul_f32 v[56:57], v[56:57], v[162:163]
	v_pk_mul_f32 v[58:59], v[58:59], v[164:165]
	v_cvt_pk_bf16_f32 v52, v60, v61
	v_cvt_pk_bf16_f32 v53, v62, v63
	v_cvt_pk_bf16_f32 v54, v56, v57
	v_cvt_pk_bf16_f32 v55, v58, v59
	s_mov_b32 s50, 0xb0000
	v_lshl_add_u64 v[48:49], v[152:153], 0, s[50:51]
	global_store_dwordx4 v[48:49], v[52:55], off
	v_mul_f32_e32 v154, 0xbfb8aa3b, v241
	v_mul_f32_e32 v156, v241, v241
	v_rcp_f32_e32 v156, v156
	v_pk_mul_f32 v[158:159], v[36:37], v[154:155] op_sel_hi:[1,0]
	v_pk_mul_f32 v[160:161], v[38:39], v[154:155] op_sel_hi:[1,0]
	v_pk_mul_f32 v[162:163], v[32:33], v[154:155] op_sel_hi:[1,0]
	v_pk_mul_f32 v[164:165], v[34:35], v[154:155] op_sel_hi:[1,0]
	v_exp_f32_e32 v158, v158
	v_exp_f32_e32 v159, v159
	v_exp_f32_e32 v160, v160
	v_exp_f32_e32 v161, v161
	v_exp_f32_e32 v162, v162
	v_exp_f32_e32 v163, v163
	v_exp_f32_e32 v164, v164
	v_exp_f32_e32 v165, v165
	v_pk_mul_f32 v[44:45], v[36:37], v[44:45]
	v_pk_mul_f32 v[46:47], v[38:39], v[46:47]
	v_pk_mul_f32 v[40:41], v[32:33], v[40:41]
	v_pk_mul_f32 v[42:43], v[34:35], v[42:43]
	v_pk_fma_f32 v[158:159], v[158:159], v[156:157], v[156:157] op_sel_hi:[1,0,0]
	v_pk_fma_f32 v[160:161], v[160:161], v[156:157], v[156:157] op_sel_hi:[1,0,0]
	v_pk_fma_f32 v[162:163], v[162:163], v[156:157], v[156:157] op_sel_hi:[1,0,0]
	v_pk_fma_f32 v[164:165], v[164:165], v[156:157], v[156:157] op_sel_hi:[1,0,0]
	v_rcp_f32_e32 v158, v158
	v_rcp_f32_e32 v159, v159
	v_rcp_f32_e32 v160, v160
	v_rcp_f32_e32 v161, v161
	v_rcp_f32_e32 v162, v162
	v_rcp_f32_e32 v163, v163
	v_rcp_f32_e32 v164, v164
	v_rcp_f32_e32 v165, v165
	v_pk_mul_f32 v[44:45], v[44:45], v[158:159]
	v_pk_mul_f32 v[46:47], v[46:47], v[160:161]
	v_pk_mul_f32 v[40:41], v[40:41], v[162:163]
	v_pk_mul_f32 v[42:43], v[42:43], v[164:165]
	v_cvt_pk_bf16_f32 v36, v44, v45
	v_cvt_pk_bf16_f32 v37, v46, v47
	v_cvt_pk_bf16_f32 v38, v40, v41
	v_cvt_pk_bf16_f32 v39, v42, v43
	s_mov_b32 s50, 0xc6000
	v_lshl_add_u64 v[32:33], v[152:153], 0, s[50:51]
	global_store_dwordx4 v[32:33], v[36:39], off
	v_mul_f32_e32 v154, 0xbfb8aa3b, v242
	v_mul_f32_e32 v156, v242, v242
	v_rcp_f32_e32 v156, v156
	v_pk_mul_f32 v[158:159], v[20:21], v[154:155] op_sel_hi:[1,0]
	v_pk_mul_f32 v[160:161], v[22:23], v[154:155] op_sel_hi:[1,0]
	v_pk_mul_f32 v[162:163], v[16:17], v[154:155] op_sel_hi:[1,0]
	v_pk_mul_f32 v[164:165], v[18:19], v[154:155] op_sel_hi:[1,0]
	v_exp_f32_e32 v158, v158
	v_exp_f32_e32 v159, v159
	v_exp_f32_e32 v160, v160
	v_exp_f32_e32 v161, v161
	v_exp_f32_e32 v162, v162
	v_exp_f32_e32 v163, v163
	v_exp_f32_e32 v164, v164
	v_exp_f32_e32 v165, v165
	v_pk_mul_f32 v[28:29], v[20:21], v[28:29]
	v_pk_mul_f32 v[30:31], v[22:23], v[30:31]
	v_pk_mul_f32 v[24:25], v[16:17], v[24:25]
	v_pk_mul_f32 v[26:27], v[18:19], v[26:27]
	v_pk_fma_f32 v[158:159], v[158:159], v[156:157], v[156:157] op_sel_hi:[1,0,0]
	v_pk_fma_f32 v[160:161], v[160:161], v[156:157], v[156:157] op_sel_hi:[1,0,0]
	v_pk_fma_f32 v[162:163], v[162:163], v[156:157], v[156:157] op_sel_hi:[1,0,0]
	v_pk_fma_f32 v[164:165], v[164:165], v[156:157], v[156:157] op_sel_hi:[1,0,0]
	v_rcp_f32_e32 v158, v158
	v_rcp_f32_e32 v159, v159
	v_rcp_f32_e32 v160, v160
	v_rcp_f32_e32 v161, v161
	v_rcp_f32_e32 v162, v162
	v_rcp_f32_e32 v163, v163
	v_rcp_f32_e32 v164, v164
	v_rcp_f32_e32 v165, v165
	v_pk_mul_f32 v[28:29], v[28:29], v[158:159]
	v_pk_mul_f32 v[30:31], v[30:31], v[160:161]
	v_pk_mul_f32 v[24:25], v[24:25], v[162:163]
	v_pk_mul_f32 v[26:27], v[26:27], v[164:165]
	v_cvt_pk_bf16_f32 v20, v28, v29
	v_cvt_pk_bf16_f32 v21, v30, v31
	v_cvt_pk_bf16_f32 v22, v24, v25
	v_cvt_pk_bf16_f32 v23, v26, v27
	s_mov_b32 s50, 0xdc000
	v_lshl_add_u64 v[16:17], v[152:153], 0, s[50:51]
	global_store_dwordx4 v[16:17], v[20:23], off
	v_mul_f32_e32 v154, 0xbfb8aa3b, v243
	v_mul_f32_e32 v156, v243, v243
	v_rcp_f32_e32 v156, v156
	v_pk_mul_f32 v[158:159], v[4:5], v[154:155] op_sel_hi:[1,0]
	v_pk_mul_f32 v[160:161], v[6:7], v[154:155] op_sel_hi:[1,0]
	v_pk_mul_f32 v[162:163], v[0:1], v[154:155] op_sel_hi:[1,0]
	v_pk_mul_f32 v[164:165], v[2:3], v[154:155] op_sel_hi:[1,0]
	v_exp_f32_e32 v158, v158
	v_exp_f32_e32 v159, v159
	v_exp_f32_e32 v160, v160
	v_exp_f32_e32 v161, v161
	v_exp_f32_e32 v162, v162
	v_exp_f32_e32 v163, v163
	v_exp_f32_e32 v164, v164
	v_exp_f32_e32 v165, v165
	v_pk_mul_f32 v[12:13], v[4:5], v[12:13]
	v_pk_mul_f32 v[14:15], v[6:7], v[14:15]
	v_pk_mul_f32 v[8:9], v[0:1], v[8:9]
	v_pk_mul_f32 v[10:11], v[2:3], v[10:11]
	v_pk_fma_f32 v[158:159], v[158:159], v[156:157], v[156:157] op_sel_hi:[1,0,0]
	v_pk_fma_f32 v[160:161], v[160:161], v[156:157], v[156:157] op_sel_hi:[1,0,0]
	v_pk_fma_f32 v[162:163], v[162:163], v[156:157], v[156:157] op_sel_hi:[1,0,0]
	v_pk_fma_f32 v[164:165], v[164:165], v[156:157], v[156:157] op_sel_hi:[1,0,0]
	v_rcp_f32_e32 v158, v158
	v_rcp_f32_e32 v159, v159
	v_rcp_f32_e32 v160, v160
	v_rcp_f32_e32 v161, v161
	v_rcp_f32_e32 v162, v162
	v_rcp_f32_e32 v163, v163
	v_rcp_f32_e32 v164, v164
	v_rcp_f32_e32 v165, v165
	v_pk_mul_f32 v[12:13], v[12:13], v[158:159]
	v_pk_mul_f32 v[14:15], v[14:15], v[160:161]
	v_pk_mul_f32 v[8:9], v[8:9], v[162:163]
	v_pk_mul_f32 v[10:11], v[10:11], v[164:165]
	v_cvt_pk_bf16_f32 v4, v12, v13
	v_cvt_pk_bf16_f32 v5, v14, v15
	v_cvt_pk_bf16_f32 v6, v8, v9
	v_cvt_pk_bf16_f32 v7, v10, v11
	s_mov_b32 s50, 0xf2000
	v_lshl_add_u64 v[0:1], v[152:153], 0, s[50:51]
	global_store_dwordx4 v[0:1], v[4:7], off
	s_mov_b64 s[40:41], 0
